# gate-GEMM mid-K rescale: 32 serialized global loads software-pipelined 7 rounds deep (hand-written); MLA loop wave-uniform exec-mask branches turned into scalar branches
# speedup vs baseline: 1.0313x; 1.0118x over previous
; #define MFMA32(a, b, c) __builtin_amdgcn_mfma_f32_32x32x16_bf16((a), (b), (c), 0, 0, 0)
; #define PV_IDX(g) (((g) & 1) * 4 + PV_KS(g))
; template <int DQK, int DV, bool MLA>
; __device__ __forceinline__ void attn_pass(LAS unsigned char* lds, const bf16_t* Qrow, const bf16_t* K0, int pitchK, const bf16_t* KrB, const bf16_t* Vt0, int NT, int q0w,
;                                           f32x16 (&o)[DV / 32], float& l_out, int tid) {
;     ...
;         if (64 * t <= q0w + 31) {
;     ...
;         } else if (pend) {
;             bf16x8 vf[8];
; #pragma unroll
;             for (int g = 0; g < 8; ++g) vf[PV_IDX(g)] = VFRAG(vp, PV_D(g), PV_KS(g));
; #pragma unroll
;             for (int g = 0; g < NG; ++g) {
;                 o[PV_D(g)] = MFMA32(vf[PV_IDX(g)], pf[PV_KS(g)], o[PV_D(g)]);
;                 if (NDV == 4 && g < 8) vf[PV_IDX(g)] = VFRAG(vp, PV_D(g) + 2, PV_KS(g));
;             }
;             pend = false;
;         }
.LBB0_63:
	v_lshl_add_u32 v214, s6, 13, v222
	s_sub_i32 s6, s90, 63
	v_readfirstlane_b32 s7, v221
	s_cmp_le_i32 s6, s7
	s_cselect_b64 s[44:45], -1, 0
	s_cbranch_scc1 .LBB0_70
	s_mov_b64 s[6:7], 0
	s_and_saveexec_b64 s[14:15], s[48:49]
	s_cbranch_execz .LBB0_66
	v_add_u32_e32 v54, v214, v244
	ds_read_b128 v[50:53], v54 offset:49152
	s_waitcnt lgkmcnt(0)
	v_mfma_f32_32x32x16_bf16 v[18:33], v[50:53], v[158:161], v[18:33]
	ds_read_b128 v[50:53], v54 offset:53248
	v_add_u32_e32 v54, v214, v251
	s_waitcnt lgkmcnt(0)
	v_mfma_f32_32x32x16_bf16 v[2:17], v[50:53], v[158:161], v[2:17]
	ds_read_b128 v[50:53], v54 offset:49152
	s_waitcnt lgkmcnt(0)
	v_mfma_f32_32x32x16_bf16 v[18:33], v[50:53], v[162:165], v[18:33]
	ds_read_b128 v[50:53], v54 offset:53248
	v_add_u32_e32 v54, v214, v250
	s_waitcnt lgkmcnt(0)
	v_mfma_f32_32x32x16_bf16 v[2:17], v[50:53], v[162:165], v[2:17]
	ds_read_b128 v[50:53], v54 offset:49152
	s_waitcnt lgkmcnt(0)
	v_mfma_f32_32x32x16_bf16 v[18:33], v[50:53], v[166:169], v[18:33]
	ds_read_b128 v[50:53], v54 offset:53248
	v_add_u32_e32 v54, v214, v249
	s_waitcnt lgkmcnt(0)
	v_mfma_f32_32x32x16_bf16 v[2:17], v[50:53], v[166:169], v[2:17]
	ds_read_b128 v[50:53], v54 offset:49152
	s_waitcnt lgkmcnt(0)
	v_mfma_f32_32x32x16_bf16 v[18:33], v[50:53], v[154:157], v[18:33]
	ds_read_b128 v[50:53], v54 offset:53248
	s_waitcnt lgkmcnt(0)
	v_mfma_f32_32x32x16_bf16 v[2:17], v[50:53], v[154:157], v[2:17]

; #define MFMA32(a, b, c) __builtin_amdgcn_mfma_f32_32x32x16_bf16((a), (b), (c), 0, 0, 0)
; #define PV_IDX(g) (((g) & 1) * 4 + PV_KS(g))
; template <int DQK, int DV, bool MLA>
; __device__ __forceinline__ void attn_pass(LAS unsigned char* lds, const bf16_t* Qrow, const bf16_t* K0, int pitchK, const bf16_t* KrB, const bf16_t* Vt0, int NT, int q0w,
;                                           f32x16 (&o)[DV / 32], float& l_out, int tid) {
;     ...
;             __builtin_amdgcn_s_setprio(1);
; #pragma unroll
;             for (int d0 = 0; d0 < ND; ++d0) { s0 = MFMA32(kf[2 * d0], q[d0], s0); s1 = MFMA32(kf[2 * d0 + 1], q[d0], s1); }
;             __builtin_amdgcn_s_setprio(0);
;             __builtin_amdgcn_sched_barrier(0);
;             if (t + 1 < NT) ATT_KLOAD((t + 1) & 3);
;             bf16x8 vf[8];
;             if (pend) {
; #pragma unroll
;                 for (int g = 0; g < 8; ++g) vf[PV_IDX(g)] = VFRAG(vp, PV_D(g), PV_KS(g));
;             }
.LBB0_70:
	s_setprio 1
	s_waitcnt lgkmcnt(0)
	v_mfma_f32_32x32x16_bf16 v[66:81], v[150:153], v[82:85], v[34:49]
	v_mfma_f32_32x32x16_bf16 v[50:65], v[146:149], v[82:85], v[34:49]
	v_mfma_f32_32x32x16_bf16 v[66:81], v[142:145], v[86:89], v[66:81]
	v_mfma_f32_32x32x16_bf16 v[50:65], v[138:141], v[86:89], v[50:65]
	v_mfma_f32_32x32x16_bf16 v[66:81], v[134:137], v[90:93], v[66:81]
	v_mfma_f32_32x32x16_bf16 v[50:65], v[130:133], v[90:93], v[50:65]
	v_mfma_f32_32x32x16_bf16 v[66:81], v[126:129], v[94:97], v[66:81]
	v_mfma_f32_32x32x16_bf16 v[50:65], v[122:125], v[94:97], v[50:65]
	v_mfma_f32_32x32x16_bf16 v[66:81], v[114:117], v[98:101], v[66:81]
	v_mfma_f32_32x32x16_bf16 v[50:65], v[110:113], v[98:101], v[50:65]
	v_mfma_f32_32x32x16_bf16 v[66:81], v[118:121], v[102:105], v[66:81]
	v_mfma_f32_32x32x16_bf16 v[50:65], v[106:109], v[102:105], v[50:65]
	s_setprio 0
	v_add_u32_e32 v170, v214, v244
	v_add_u32_e32 v174, v214, v251
	v_add_u32_e32 v182, v214, v250
	v_add_u32_e32 v190, v214, v249
	ds_read_b128 v[178:181], v170 offset:49152
	ds_read_b128 v[170:173], v170 offset:53248
	ds_read_b128 v[186:189], v174 offset:49152
	ds_read_b128 v[174:177], v174 offset:53248
	ds_read_b128 v[194:197], v182 offset:49152
	ds_read_b128 v[182:185], v182 offset:53248
	ds_read_b128 v[198:201], v190 offset:49152
	ds_read_b128 v[190:193], v190 offset:53248
	s_add_i32 s6, s57, 5
	s_and_b32 s6, s6, 3
	v_lshl_add_u32 v106, s6, 13, v246
	v_add_u32_e32 v108, v106, v244
	ds_read_b128 v[150:153], v108
	ds_read_b128 v[146:149], v108 offset:4096
	v_add_u32_e32 v108, v106, v251
	v_lshl_add_u32 v107, s6, 12, v247
	ds_read_b128 v[142:145], v108
	ds_read_b128 v[138:141], v108 offset:4096
	v_add_u32_e32 v108, v106, v250
	v_add_u32_e32 v106, v106, v249
	ds_read_b128 v[134:137], v108
	ds_read_b128 v[130:133], v108 offset:4096
	ds_read_b128 v[126:129], v106
	ds_read_b128 v[122:125], v106 offset:4096
	v_add_u32_e32 v106, v107, v245
	v_add_u32_e32 v118, v107, v248
	ds_read_b128 v[114:117], v106 offset:32768
	ds_read_b128 v[110:113], v106 offset:34816
	ds_read_b128 v[106:109], v118 offset:34816
	ds_read_b128 v[118:121], v118 offset:32768
; #define MFMA32(a, b, c) __builtin_amdgcn_mfma_f32_32x32x16_bf16((a), (b), (c), 0, 0, 0)
; __device__ __forceinline__ float max3f(float a, float b, float c) { float r; asm("v_max3_f32 %0, %1, %2, %3" : "=v"(r) : "v"(a), "v"(b), "v"(c)); return r; }
; __device__ __forceinline__ float xhalf_max(float v) { auto rr = __builtin_amdgcn_permlane32_swap(__float_as_uint(v), __float_as_uint(v), false, false); return __builtin_fmaxf(__uint_as_float(rr[0]), __uint_as_float(rr[1])); }
; #define PV_IDX(g) (((g) & 1) * 4 + PV_KS(g))
; template <int DQK, int DV, bool MLA>
; __device__ __forceinline__ void attn_pass(LAS unsigned char* lds, const bf16_t* Qrow, const bf16_t* K0, int pitchK, const bf16_t* KrB, const bf16_t* Vt0, int NT, int q0w,
;                                           f32x16 (&o)[DV / 32], float& l_out, int tid) {
;     ...
;             if (64 * t + 63 > q0w) {
;                 int hi_l = hi; asm volatile("" : "+v"(hi_l));
;                 const int qrow = q0w + r32, kb0 = 64 * t + 4 * hi_l;
; #pragma unroll
;                 for (int r = 0; r < 16; ++r) { const int kv = kb0 + (r & 3) + 8 * (r >> 2); if (kv > qrow) s0[r] = -INFINITY; if (kv + 32 > qrow) s1[r] = -INFINITY; }
;             }
;             float mx;
;             asm volatile("s_nop 11" : "+v"(s0), "+v"(s1));
;             {
;                 float a = max3f(s0[0], s0[1], s1[0]), b = max3f(s0[2], s0[3], s1[1]); a = max3f(a, s1[2], s1[3]);
; #pragma unroll
;                 for (int r = 4; r < 16; r += 4) { a = max3f(a, s0[r], s0[r + 1]); b = max3f(b, s0[r + 2], s0[r + 3]); a = max3f(a, s1[r], s1[r + 1]); b = max3f(b, s1[r + 2], s1[r + 3]); }
;                 mx = xhalf_max(__builtin_fmaxf(a, b)) - (MLA ? 0.f : m);
;             }
;             if (t == 0 || __any(mx > THR)) {
;                 if (pend) {
; #pragma unroll
;                     for (int g = 0; g < NG; ++g) {
;                         o[PV_D(g)] = MFMA32(vf[PV_IDX(g)], pf[PV_KS(g)], o[PV_D(g)]);
;                         if (NDV == 4 && g < 8) vf[PV_IDX(g)] = VFRAG(vp, PV_D(g) + 2, PV_KS(g));
;                     }
.LBB0_72:
	s_add_i32 s6, s90, 31
	s_cmp_gt_i32 s6, s7
	s_cbranch_scc0 .LBB0_76
	v_mov_b32_e32 v214, v239
	s_nop 0
	v_lshl_add_u32 v214, v214, 2, s90
	v_subrev_u32_e32 v223, 31, v214
	v_subrev_u32_e32 v215, 63, v214
	v_cmp_le_i32_e32 vcc, v223, v252
	s_nop 1
	v_cndmask_b32_e32 v50, v220, v50, vcc
	v_cmp_lt_i32_e32 vcc, v215, v252
	s_nop 1
	v_cndmask_b32_e32 v67, v220, v67, vcc
	v_cmp_le_i32_e32 vcc, v215, v252
	v_subrev_u32_e32 v215, 30, v214
	s_nop 0
	v_cndmask_b32_e32 v66, v220, v66, vcc
	v_cmp_le_i32_e32 vcc, v215, v252
	v_subrev_u32_e32 v215, 61, v214
	s_nop 0
	v_cndmask_b32_e32 v51, v220, v51, vcc
	v_cmp_le_i32_e32 vcc, v215, v252
	v_subrev_u32_e32 v215, 29, v214
	s_nop 0
	v_cndmask_b32_e32 v68, v220, v68, vcc
	v_cmp_le_i32_e32 vcc, v215, v252
	v_subrev_u32_e32 v215, 60, v214
	s_nop 0
	v_cndmask_b32_e32 v52, v220, v52, vcc
	v_cmp_le_i32_e32 vcc, v215, v252
	v_subrev_u32_e32 v215, 28, v214
	s_nop 0
	v_cndmask_b32_e32 v69, v220, v69, vcc
	v_cmp_le_i32_e32 vcc, v215, v252
	v_subrev_u32_e32 v215, 55, v214
	s_nop 0
	v_cndmask_b32_e32 v53, v220, v53, vcc
	v_cmp_le_i32_e32 vcc, v215, v252
	v_subrev_u32_e32 v215, 23, v214
	s_nop 0
	v_cndmask_b32_e32 v70, v220, v70, vcc
	v_cmp_le_i32_e32 vcc, v215, v252
	v_subrev_u32_e32 v215, 54, v214
	s_nop 0
	v_cndmask_b32_e32 v54, v220, v54, vcc
	v_cmp_le_i32_e32 vcc, v215, v252
	v_subrev_u32_e32 v215, 22, v214
	s_nop 0
	v_cndmask_b32_e32 v71, v220, v71, vcc
	v_cmp_le_i32_e32 vcc, v215, v252
	v_subrev_u32_e32 v215, 53, v214
	s_nop 0
	v_cndmask_b32_e32 v55, v220, v55, vcc
	v_cmp_le_i32_e32 vcc, v215, v252
	v_subrev_u32_e32 v215, 21, v214
	s_nop 0
	v_cndmask_b32_e32 v72, v220, v72, vcc
	v_cmp_le_i32_e32 vcc, v215, v252
	v_subrev_u32_e32 v215, 52, v214
	s_nop 0
	v_cndmask_b32_e32 v56, v220, v56, vcc
	v_cmp_le_i32_e32 vcc, v215, v252
	v_subrev_u32_e32 v215, 20, v214
	s_nop 0
	v_cndmask_b32_e32 v73, v220, v73, vcc
	v_cmp_le_i32_e32 vcc, v215, v252
	v_subrev_u32_e32 v215, 47, v214
	s_nop 0
	v_cndmask_b32_e32 v57, v220, v57, vcc
	v_cmp_le_i32_e32 vcc, v215, v252
	v_add_u32_e32 v215, -15, v214
	s_nop 0
	v_cndmask_b32_e32 v74, v220, v74, vcc
	v_cmp_le_i32_e32 vcc, v215, v252
	v_subrev_u32_e32 v215, 46, v214
	s_nop 0
	v_cndmask_b32_e32 v58, v220, v58, vcc
	v_cmp_le_i32_e32 vcc, v215, v252
	v_add_u32_e32 v215, -14, v214
	s_nop 0
	v_cndmask_b32_e32 v75, v220, v75, vcc
	v_cmp_le_i32_e32 vcc, v215, v252
	v_subrev_u32_e32 v215, 45, v214
	s_nop 0
	v_cndmask_b32_e32 v59, v220, v59, vcc
	v_cmp_le_i32_e32 vcc, v215, v252
	v_add_u32_e32 v215, -13, v214
	s_nop 0
	v_cndmask_b32_e32 v76, v220, v76, vcc
	v_cmp_le_i32_e32 vcc, v215, v252
	v_subrev_u32_e32 v215, 44, v214
	s_nop 0
	v_cndmask_b32_e32 v60, v220, v60, vcc
	v_cmp_le_i32_e32 vcc, v215, v252
	v_add_u32_e32 v215, -12, v214
	s_nop 0
	v_cndmask_b32_e32 v77, v220, v77, vcc
	v_cmp_le_i32_e32 vcc, v215, v252
	v_subrev_u32_e32 v215, 39, v214
	s_nop 0
	v_cndmask_b32_e32 v61, v220, v61, vcc
	v_cmp_le_i32_e32 vcc, v215, v252
	v_add_u32_e32 v215, -7, v214
	s_nop 0
	v_cndmask_b32_e32 v78, v220, v78, vcc
	v_cmp_le_i32_e32 vcc, v215, v252
	v_subrev_u32_e32 v215, 38, v214
	s_nop 0
	v_cndmask_b32_e32 v62, v220, v62, vcc
	v_cmp_le_i32_e32 vcc, v215, v252
	v_add_u32_e32 v215, -6, v214
	s_nop 0
	v_cndmask_b32_e32 v79, v220, v79, vcc
	v_cmp_le_i32_e32 vcc, v215, v252
	v_subrev_u32_e32 v215, 37, v214
	s_nop 0
	v_cndmask_b32_e32 v63, v220, v63, vcc
	v_cmp_le_i32_e32 vcc, v215, v252
	v_add_u32_e32 v215, -5, v214
	s_nop 0
	v_cndmask_b32_e32 v80, v220, v80, vcc
	v_cmp_le_i32_e32 vcc, v215, v252
	v_subrev_u32_e32 v215, 36, v214
	v_add_u32_e32 v214, -4, v214
	v_cndmask_b32_e32 v64, v220, v64, vcc
	v_cmp_le_i32_e32 vcc, v215, v252
	s_nop 1
	v_cndmask_b32_e32 v81, v220, v81, vcc
	v_cmp_le_i32_e32 vcc, v214, v252
	s_nop 1
	v_cndmask_b32_e32 v65, v220, v65, vcc
.LBB0_76:
	v_max3_f32 v214, v66, v67, v50
	v_max3_f32 v215, v68, v69, v51
	v_max3_f32 v214, v214, v52, v53
	v_max3_f32 v215, v215, v72, v73
	v_max3_f32 v214, v214, v70, v71
	v_max3_f32 v215, v215, v56, v57
	v_max3_f32 v214, v214, v54, v55
	v_max3_f32 v215, v215, v76, v77
	v_max3_f32 v214, v214, v74, v75
	v_max3_f32 v215, v215, v60, v61
	v_max3_f32 v214, v214, v58, v59
	v_max3_f32 v215, v215, v80, v81
	v_max3_f32 v214, v214, v78, v79
	v_max3_f32 v215, v215, v64, v65
	v_max3_f32 v214, v214, v62, v63
	v_max_f32_e32 v214, v214, v215
	v_mov_b32_e32 v215, v214
	s_nop 1
	v_permlane32_swap_b32_e32 v214, v215
	v_max_f32_e32 v214, v214, v215
	v_cmp_lt_f32_e32 vcc, s66, v214
	s_cbranch_vccz .LBB0_80
	s_and_saveexec_b64 s[6:7], s[48:49]
	s_cbranch_execz .LBB0_79
	s_waitcnt lgkmcnt(15)
	v_mfma_f32_32x32x16_bf16 v[18:33], v[178:181], v[158:161], v[18:33]
	s_waitcnt lgkmcnt(15)
	v_mfma_f32_32x32x16_bf16 v[2:17], v[170:173], v[158:161], v[2:17]
	s_waitcnt lgkmcnt(15)
	v_mfma_f32_32x32x16_bf16 v[18:33], v[186:189], v[162:165], v[18:33]
	s_waitcnt lgkmcnt(15)
	v_mfma_f32_32x32x16_bf16 v[2:17], v[174:177], v[162:165], v[2:17]
	s_waitcnt lgkmcnt(15)
	v_mfma_f32_32x32x16_bf16 v[18:33], v[194:197], v[166:169], v[18:33]
	s_waitcnt lgkmcnt(14)
	v_mfma_f32_32x32x16_bf16 v[2:17], v[182:185], v[166:169], v[2:17]
	s_waitcnt lgkmcnt(13)
	v_mfma_f32_32x32x16_bf16 v[18:33], v[198:201], v[154:157], v[18:33]
	s_waitcnt lgkmcnt(12)
	v_mfma_f32_32x32x16_bf16 v[2:17], v[190:193], v[154:157], v[2:17]

; #define MFMA32(a, b, c) __builtin_amdgcn_mfma_f32_32x32x16_bf16((a), (b), (c), 0, 0, 0)
; #define PV_IDX(g) (((g) & 1) * 4 + PV_KS(g))
; template <int DQK, int DV, bool MLA>
; __device__ __forceinline__ void attn_pass(LAS unsigned char* lds, const bf16_t* Qrow, const bf16_t* K0, int pitchK, const bf16_t* KrB, const bf16_t* Vt0, int NT, int q0w,
;                                           f32x16 (&o)[DV / 32], float& l_out, int tid) {
;     ...
;             float ps = 0.f;
;             u32x4 pw[4];
;             float ps1 = 0.f;
;             if (pend) {
; #pragma unroll
;                 for (int g = 0; g <= NG; ++g) {
;                     if (g < NG) {
;                         o[PV_D(g)] = MFMA32(vf[PV_IDX(g)], pf[PV_KS(g)], o[PV_D(g)]);
;                         if (NDV == 4 && g < 8) vf[PV_IDX(g)] = VFRAG(vp, PV_D(g) + 2, PV_KS(g));
; #pragma unroll
;                         for (int e = g * EPG; e < (g + 1) * EPG; ++e) { if (e < 16) s0[e] = __builtin_amdgcn_exp2f(MLA ? s0[e] : s0[e] - m); else s1[e - 16] = __builtin_amdgcn_exp2f(MLA ? s1[e - 16] : s1[e - 16] - m); }
;                     }
;                     if (g > 0) {
; #pragma unroll
;                         for (int e = (g - 1) * EPG; e < g * EPG; ++e) {
;                             const float v = e < 16 ? s0[e] : s1[e - 16];
;                             if (e & 1) ps1 += v; else ps += v;
;                             if (e & 1) { const int j = e >> 1; pw[j >> 2][j & 3] = e < 16 ? cvtpk(s0[e - 1], s0[e]) : cvtpk(s1[e - 17], s1[e - 16]); }
;                         }
;                     }
;                     __builtin_amdgcn_sched_barrier(0);
;                 }
;             } else {
;                 float m2 = MLA ? 0.f : m; asm volatile("" : "+v"(m2));
; #pragma unroll
;                 for (int e = 0; e < 32; ++e) {
;                     if (e < 16) { s0[e] = __builtin_amdgcn_exp2f(MLA ? s0[e] + m2 : s0[e] - m2); ps += s0[e]; } else { s1[e - 16] = __builtin_amdgcn_exp2f(MLA ? s1[e - 16] + m2 : s1[e - 16] - m2); ps += s1[e - 16]; }
;                     if (e & 1) { const int j = e >> 1; pw[j >> 2][j & 3] = e < 16 ? cvtpk(s0[e - 1], s0[e]) : cvtpk(s1[e - 17], s1[e - 16]); }
;                 }
;             }
;             l += ps + ps1;
; #pragma unroll
;             for (int k = 0; k < 4; ++k) pf[k] = __builtin_bit_cast(bf16x8, pw[k]);
;             pend = true;
.LBB0_80:
	s_cmp_lg_u32 s48, 0
	s_cbranch_scc1 .Lmla_woven
	v_mov_b32_e32 v156, 0
	s_nop 0
	v_add_f32_e32 v66, v66, v156
	v_exp_f32_e32 v66, v66
	v_add_f32_e32 v67, v67, v156
	v_exp_f32_e32 v67, v67
	v_add_f32_e32 v50, v50, v156
	v_add_f32_e32 v154, 0, v66
	v_exp_f32_e32 v50, v50
	v_cvt_pk_bf16_f32 v158, v66, v67
	v_add_f32_e32 v66, v67, v154
	v_add_f32_e32 v67, v68, v156
	v_add_f32_e32 v68, v69, v156
	v_exp_f32_e32 v67, v67
	v_exp_f32_e32 v68, v68
	v_add_f32_e32 v69, v70, v156
	v_exp_f32_e32 v69, v69
	v_add_f32_e32 v66, v67, v66
	v_cvt_pk_bf16_f32 v159, v67, v68
	v_add_f32_e32 v67, v71, v156
	v_add_f32_e32 v66, v68, v66
	v_exp_f32_e32 v67, v67
	v_add_f32_e32 v68, v72, v156
	v_add_f32_e32 v70, v73, v156
	v_exp_f32_e32 v68, v68
	v_exp_f32_e32 v70, v70
	v_add_f32_e32 v66, v69, v66
	v_add_f32_e32 v66, v67, v66
	v_cvt_pk_bf16_f32 v160, v69, v67
	v_add_f32_e32 v66, v68, v66
	v_cvt_pk_bf16_f32 v161, v68, v70
	v_add_f32_e32 v67, v74, v156
	v_add_f32_e32 v68, v75, v156
	v_exp_f32_e32 v67, v67
	v_exp_f32_e32 v68, v68
	v_add_f32_e32 v66, v70, v66
	v_add_f32_e32 v69, v76, v156
	v_exp_f32_e32 v69, v69
	v_add_f32_e32 v66, v67, v66
	v_cvt_pk_bf16_f32 v162, v67, v68
	v_add_f32_e32 v67, v77, v156
	v_add_f32_e32 v66, v68, v66
	v_exp_f32_e32 v67, v67
	v_add_f32_e32 v68, v78, v156
	v_add_f32_e32 v70, v79, v156
	v_exp_f32_e32 v68, v68
	v_exp_f32_e32 v70, v70
	v_add_f32_e32 v66, v69, v66
	v_add_f32_e32 v66, v67, v66
	v_cvt_pk_bf16_f32 v163, v69, v67
	v_add_f32_e32 v67, v80, v156
	v_add_f32_e32 v66, v68, v66
	v_cvt_pk_bf16_f32 v164, v68, v70
	v_exp_f32_e32 v67, v67
	v_add_f32_e32 v68, v81, v156
	v_exp_f32_e32 v68, v68
	v_add_f32_e32 v51, v51, v156
	v_add_f32_e32 v66, v70, v66
	v_exp_f32_e32 v51, v51
	v_add_f32_e32 v52, v52, v156
	v_add_f32_e32 v53, v53, v156
	v_add_f32_e32 v66, v67, v66
	v_exp_f32_e32 v52, v52
	v_exp_f32_e32 v53, v53
	v_add_f32_e32 v66, v68, v66
	v_add_f32_e32 v66, v50, v66
	v_add_f32_e32 v66, v51, v66
	v_cvt_pk_bf16_f32 v166, v50, v51
	v_add_f32_e32 v50, v52, v66
	v_cvt_pk_bf16_f32 v167, v52, v53
	v_add_f32_e32 v51, v54, v156
	v_add_f32_e32 v52, v55, v156
	v_exp_f32_e32 v51, v51
	v_exp_f32_e32 v52, v52
	v_add_f32_e32 v50, v53, v50
	v_add_f32_e32 v53, v56, v156
	v_exp_f32_e32 v53, v53
	v_add_f32_e32 v50, v51, v50
	v_cvt_pk_bf16_f32 v168, v51, v52
	v_add_f32_e32 v51, v57, v156
	v_add_f32_e32 v50, v52, v50
	v_exp_f32_e32 v51, v51
	v_add_f32_e32 v52, v58, v156
	v_add_f32_e32 v54, v59, v156
	v_exp_f32_e32 v52, v52
	v_exp_f32_e32 v54, v54
	v_add_f32_e32 v50, v53, v50
	v_add_f32_e32 v50, v51, v50
	v_cvt_pk_bf16_f32 v169, v53, v51
	v_add_f32_e32 v50, v52, v50
	v_cvt_pk_bf16_f32 v154, v52, v54
	v_add_f32_e32 v51, v60, v156
	v_add_f32_e32 v52, v61, v156
	v_exp_f32_e32 v51, v51
	v_exp_f32_e32 v52, v52
	v_add_f32_e32 v50, v54, v50
	v_add_f32_e32 v53, v62, v156
	v_exp_f32_e32 v53, v53
	v_add_f32_e32 v50, v51, v50
	v_cvt_pk_bf16_f32 v155, v51, v52
	v_add_f32_e32 v51, v63, v156
	v_add_f32_e32 v50, v52, v50
	v_exp_f32_e32 v51, v51
	v_add_f32_e32 v52, v64, v156
	v_exp_f32_e32 v52, v52
	v_add_f32_e32 v54, v65, v156
	v_exp_f32_e32 v54, v54
	v_add_f32_e32 v50, v53, v50
	v_add_f32_e32 v50, v51, v50
	v_add_f32_e32 v50, v52, v50
	v_cvt_pk_bf16_f32 v165, v67, v68
	v_cvt_pk_bf16_f32 v156, v53, v51
	v_add_f32_e32 v214, v54, v50
	v_cvt_pk_bf16_f32 v157, v52, v54
.LBB0_82:
	v_mov_b32_e32 v215, 0
	s_branch .LBB0_84
.Lmla_woven:
	s_waitcnt lgkmcnt(12)
	v_mfma_f32_32x32x16_bf16 v[18:33], v[178:181], v[158:161], v[18:33]
	v_exp_f32_e32 v66, v66
	v_exp_f32_e32 v67, v67
	v_exp_f32_e32 v68, v68
	v_exp_f32_e32 v69, v69
	v_mfma_f32_32x32x16_bf16 v[2:17], v[170:173], v[158:161], v[2:17]
	v_cvt_pk_bf16_f32 v158, v66, v67
	v_cvt_pk_bf16_f32 v159, v68, v69
	v_exp_f32_e32 v70, v70
	v_exp_f32_e32 v71, v71
	v_exp_f32_e32 v72, v72
	v_exp_f32_e32 v73, v73
	v_mfma_f32_32x32x16_bf16 v[18:33], v[186:189], v[162:165], v[18:33]
	v_cvt_pk_bf16_f32 v160, v70, v71
	v_cvt_pk_bf16_f32 v161, v72, v73
	v_exp_f32_e32 v74, v74
	v_exp_f32_e32 v75, v75
	v_exp_f32_e32 v76, v76
	v_exp_f32_e32 v77, v77
	v_mfma_f32_32x32x16_bf16 v[2:17], v[174:177], v[162:165], v[2:17]
	v_cvt_pk_bf16_f32 v162, v74, v75
	v_add_f32_e64 v66, v68, v66
	v_add_f32_e64 v67, v69, v67
	v_cvt_pk_bf16_f32 v163, v76, v77
	v_pk_add_f32 v[66:67], v[70:71], v[66:67]
	v_exp_f32_e32 v78, v78
	v_pk_add_f32 v[66:67], v[72:73], v[66:67]
	v_exp_f32_e32 v79, v79
	v_exp_f32_e32 v80, v80
	v_exp_f32_e32 v81, v81
	v_pk_add_f32 v[66:67], v[74:75], v[66:67]
	v_mfma_f32_32x32x16_bf16 v[18:33], v[194:197], v[166:169], v[18:33]
	v_cvt_pk_bf16_f32 v164, v78, v79
	v_cvt_pk_bf16_f32 v165, v80, v81
	v_exp_f32_e32 v50, v50
	v_exp_f32_e32 v51, v51
	v_exp_f32_e32 v52, v52
	v_exp_f32_e32 v53, v53
	v_mfma_f32_32x32x16_bf16 v[2:17], v[182:185], v[166:169], v[2:17]
	v_cvt_pk_bf16_f32 v166, v50, v51
	v_cvt_pk_bf16_f32 v167, v52, v53
	v_exp_f32_e32 v54, v54
	v_exp_f32_e32 v55, v55
	v_exp_f32_e32 v56, v56
	v_exp_f32_e32 v57, v57
	v_mfma_f32_32x32x16_bf16 v[18:33], v[198:201], v[154:157], v[18:33]
	v_cvt_pk_bf16_f32 v168, v54, v55
	v_cvt_pk_bf16_f32 v169, v56, v57
	v_exp_f32_e32 v58, v58
	v_exp_f32_e32 v59, v59
	v_exp_f32_e32 v60, v60
	v_exp_f32_e32 v61, v61
	v_mfma_f32_32x32x16_bf16 v[2:17], v[190:193], v[154:157], v[2:17]
	v_cvt_pk_bf16_f32 v154, v58, v59
	v_cvt_pk_bf16_f32 v155, v60, v61
	v_exp_f32_e32 v62, v62
	v_exp_f32_e32 v63, v63
	v_exp_f32_e32 v64, v64
	v_exp_f32_e32 v65, v65
	v_pk_add_f32 v[66:67], v[76:77], v[66:67]
	v_pk_add_f32 v[50:51], v[52:53], v[50:51]
	v_cvt_pk_bf16_f32 v156, v62, v63
	v_pk_add_f32 v[66:67], v[78:79], v[66:67]
	v_pk_add_f32 v[50:51], v[54:55], v[50:51]
	v_pk_add_f32 v[66:67], v[80:81], v[66:67]
	v_pk_add_f32 v[50:51], v[56:57], v[50:51]
	v_pk_add_f32 v[66:67], v[58:59], v[66:67]
	v_pk_add_f32 v[50:51], v[60:61], v[50:51]
	v_pk_add_f32 v[66:67], v[62:63], v[66:67]
	v_pk_add_f32 v[50:51], v[64:65], v[50:51]
	v_cvt_pk_bf16_f32 v157, v64, v65
	v_pk_add_f32 v[214:215], v[66:67], v[50:51]
.LBB0_84:
	s_cmp_lg_u32 s46, 0
	v_add_f32_e32 v50, v214, v215
	v_add_f32_e32 v207, v207, v50
	s_cbranch_scc1 .LBB0_68
	s_branch .LBB0_86

; __device__ __forceinline__ float bf_lo(unsigned w) { return __uint_as_float(w << 16); }
; __device__ __forceinline__ float bf_hi(unsigned w) { return __uint_as_float(w & 0xffff0000u); }
; template <class Epi, class Sched, bool ALIGN_EPI = false, bool SP2 = false>
; __device__ __forceinline__ void gemm_phase(PG8_LAS unsigned char* lds, const Gemm g, const Sched& S, const Epi& E) {
;     ...
;             if (E.mid_at == t) E.mid(acc, cur, wr, wc, fr, fq);
;     __device__ __forceinline__ void mid(f32x4 (&acc)[2][2][4][2], const pg8::Unit& u, int wr, int wc, int fr_, int fq_) const {
;         int fr = fr_, fq = fq_; asm volatile("" : "+v"(fr), "+v"(fq));
;         const bf16_t* gm = (const bf16_t*)(ws + WS_GM); const bf16_t* gd = (const bf16_t*)(ws + WS_GD);
;         const int rowbase = u.pm * 256 + wr * 64, cw = wc * 32 + fq * 8;
; #pragma unroll
;         for (int ai = 0; ai < 2; ++ai)
; #pragma unroll
;             for (int m = 0; m < 4; ++m) {
;                 const int row = rowbase + ai * 128 + m * 16 + fr;
; #pragma unroll
;                 for (int bj = 0; bj < 2; ++bj) {
;                     const size_t off = (size_t)row * DM + u.pn * 256 + bj * 128 + cw;
;                     const u32x4 a = *(const u32x4*)(gm + off), b = *(const u32x4*)(gd + off);
;                     f32x4 r0, r1;
;                     r0[0] = bf_lo(a.x) * __builtin_amdgcn_rcpf(fmaxf(bf_lo(b.x), 1e-30f)); r0[1] = bf_hi(a.x) * __builtin_amdgcn_rcpf(fmaxf(bf_hi(b.x), 1e-30f));
;                     r0[2] = bf_lo(a.y) * __builtin_amdgcn_rcpf(fmaxf(bf_lo(b.y), 1e-30f)); r0[3] = bf_hi(a.y) * __builtin_amdgcn_rcpf(fmaxf(bf_hi(b.y), 1e-30f));
;                     r1[0] = bf_lo(a.z) * __builtin_amdgcn_rcpf(fmaxf(bf_lo(b.z), 1e-30f)); r1[1] = bf_hi(a.z) * __builtin_amdgcn_rcpf(fmaxf(bf_hi(b.z), 1e-30f));
;                     r1[2] = bf_lo(a.w) * __builtin_amdgcn_rcpf(fmaxf(bf_lo(b.w), 1e-30f)); r1[3] = bf_hi(a.w) * __builtin_amdgcn_rcpf(fmaxf(bf_hi(b.w), 1e-30f));
;                     acc[ai][bj][m][0] *= r0; acc[ai][bj][m][1] *= r1;
;                 }
;             }
.LBB0_398:
	s_cmp_lg_u32 s13, s6
	s_cbranch_scc1 .LBB0_397
	v_add_u32_e32 v132, s2, v189
	v_lshl_add_u32 v133, v187, 3, s57
	v_add_u32_e32 v133, s92, v133
	v_lshlrev_b32_e32 v133, 1, v133
	v_lshl_add_u32 v132, v132, 11, v133
	global_load_dwordx4 v[160:163], v132, s[70:71]
	global_load_dwordx4 v[164:167], v132, s[68:69]
	v_add_u32_e32 v133, 0x100, v132
	global_load_dwordx4 v[168:171], v133, s[70:71]
	global_load_dwordx4 v[172:175], v133, s[68:69]
	v_add_u32_e32 v133, 0x8000, v132
	global_load_dwordx4 v[176:179], v133, s[70:71]
	global_load_dwordx4 v[180:183], v133, s[68:69]
	v_add_u32_e32 v133, 0x8100, v132
	global_load_dwordx4 v[194:197], v133, s[70:71]
	global_load_dwordx4 v[198:201], v133, s[68:69]
	v_add_u32_e32 v133, 0x10000, v132
	global_load_dwordx4 v[202:205], v133, s[70:71]
	global_load_dwordx4 v[206:209], v133, s[68:69]
	v_add_u32_e32 v133, 0x10100, v132
	global_load_dwordx4 v[236:239], v133, s[70:71]
	global_load_dwordx4 v[240:243], v133, s[68:69]
	v_add_u32_e32 v133, 0x18000, v132
	global_load_dwordx4 v[244:247], v133, s[70:71]
	global_load_dwordx4 v[248:251], v133, s[68:69]
	s_waitcnt vmcnt(12)
	v_lshlrev_b32_e32 v134, 16, v164
	v_and_b32_e32 v135, 0xffff0000, v164
	v_max_f32_e32 v134, 0xda24260, v134
	v_max_f32_e32 v135, 0xda24260, v135
	v_rcp_f32_e32 v134, v134
	v_rcp_f32_e32 v135, v135
	v_lshlrev_b32_e32 v136, 16, v160
	v_and_b32_e32 v137, 0xffff0000, v160
	v_lshlrev_b32_e32 v138, 16, v165
	v_and_b32_e32 v139, 0xffff0000, v165
	v_max_f32_e32 v138, 0xda24260, v138
	v_max_f32_e32 v139, 0xda24260, v139
	v_rcp_f32_e32 v138, v138
	v_rcp_f32_e32 v139, v139
	v_lshlrev_b32_e32 v144, 16, v161
	v_and_b32_e32 v145, 0xffff0000, v161
	v_pk_mul_f32 v[134:135], v[134:135], v[136:137]
	v_pk_mul_f32 v[138:139], v[138:139], v[144:145]
	v_pk_mul_f32 v[124:125], v[124:125], v[134:135]
	v_pk_mul_f32 v[126:127], v[126:127], v[138:139]
	v_lshlrev_b32_e32 v134, 16, v166
	v_and_b32_e32 v135, 0xffff0000, v166
	v_max_f32_e32 v134, 0xda24260, v134
	v_max_f32_e32 v135, 0xda24260, v135
	v_rcp_f32_e32 v134, v134
	v_rcp_f32_e32 v135, v135
	v_lshlrev_b32_e32 v136, 16, v162
	v_and_b32_e32 v137, 0xffff0000, v162
	v_lshlrev_b32_e32 v138, 16, v167
	v_and_b32_e32 v139, 0xffff0000, v167
	v_max_f32_e32 v138, 0xda24260, v138
	v_max_f32_e32 v139, 0xda24260, v139
	v_rcp_f32_e32 v138, v138
	v_rcp_f32_e32 v139, v139
	v_lshlrev_b32_e32 v144, 16, v163
	v_and_b32_e32 v145, 0xffff0000, v163
	v_pk_mul_f32 v[134:135], v[134:135], v[136:137]
	v_pk_mul_f32 v[138:139], v[138:139], v[144:145]
	v_pk_mul_f32 v[116:117], v[116:117], v[134:135]
	v_pk_mul_f32 v[118:119], v[118:119], v[138:139]
	v_add_u32_e32 v133, 0x18100, v132
	global_load_dwordx4 v[160:163], v133, s[70:71]
	global_load_dwordx4 v[164:167], v133, s[68:69]
	s_waitcnt vmcnt(12)
	v_lshlrev_b32_e32 v134, 16, v172
	v_and_b32_e32 v135, 0xffff0000, v172
	v_max_f32_e32 v134, 0xda24260, v134
	v_max_f32_e32 v135, 0xda24260, v135
	v_rcp_f32_e32 v134, v134
	v_rcp_f32_e32 v135, v135
	v_lshlrev_b32_e32 v136, 16, v168
	v_and_b32_e32 v137, 0xffff0000, v168
	v_lshlrev_b32_e32 v138, 16, v173
	v_and_b32_e32 v139, 0xffff0000, v173
	v_max_f32_e32 v138, 0xda24260, v138
	v_max_f32_e32 v139, 0xda24260, v139
	v_rcp_f32_e32 v138, v138
	v_rcp_f32_e32 v139, v139
	v_lshlrev_b32_e32 v144, 16, v169
	v_and_b32_e32 v145, 0xffff0000, v169
	v_pk_mul_f32 v[134:135], v[134:135], v[136:137]
	v_pk_mul_f32 v[138:139], v[138:139], v[144:145]
	v_pk_mul_f32 v[128:129], v[128:129], v[134:135]
	v_pk_mul_f32 v[130:131], v[130:131], v[138:139]
	v_lshlrev_b32_e32 v134, 16, v174
	v_and_b32_e32 v135, 0xffff0000, v174
	v_max_f32_e32 v134, 0xda24260, v134
	v_max_f32_e32 v135, 0xda24260, v135
	v_rcp_f32_e32 v134, v134
	v_rcp_f32_e32 v135, v135
	v_lshlrev_b32_e32 v136, 16, v170
	v_and_b32_e32 v137, 0xffff0000, v170
	v_lshlrev_b32_e32 v138, 16, v175
	v_and_b32_e32 v139, 0xffff0000, v175
	v_max_f32_e32 v138, 0xda24260, v138
	v_max_f32_e32 v139, 0xda24260, v139
	v_rcp_f32_e32 v138, v138
	v_rcp_f32_e32 v139, v139
	v_lshlrev_b32_e32 v144, 16, v171
	v_and_b32_e32 v145, 0xffff0000, v171
	v_pk_mul_f32 v[134:135], v[134:135], v[136:137]
	v_pk_mul_f32 v[138:139], v[138:139], v[144:145]
	v_pk_mul_f32 v[120:121], v[120:121], v[134:135]
	v_pk_mul_f32 v[122:123], v[122:123], v[138:139]
	v_add_u32_e32 v133, 0x40000, v132
	global_load_dwordx4 v[168:171], v133, s[70:71]
	global_load_dwordx4 v[172:175], v133, s[68:69]
	s_waitcnt vmcnt(12)
	v_lshlrev_b32_e32 v134, 16, v180
	v_and_b32_e32 v135, 0xffff0000, v180
	v_max_f32_e32 v134, 0xda24260, v134
	v_max_f32_e32 v135, 0xda24260, v135
	v_rcp_f32_e32 v134, v134
	v_rcp_f32_e32 v135, v135
	v_lshlrev_b32_e32 v136, 16, v176
	v_and_b32_e32 v137, 0xffff0000, v176
	v_lshlrev_b32_e32 v138, 16, v181
	v_and_b32_e32 v139, 0xffff0000, v181
	v_max_f32_e32 v138, 0xda24260, v138
	v_max_f32_e32 v139, 0xda24260, v139
	v_rcp_f32_e32 v138, v138
	v_rcp_f32_e32 v139, v139
	v_lshlrev_b32_e32 v144, 16, v177
	v_and_b32_e32 v145, 0xffff0000, v177
	v_pk_mul_f32 v[134:135], v[134:135], v[136:137]
	v_pk_mul_f32 v[138:139], v[138:139], v[144:145]
	v_pk_mul_f32 v[108:109], v[108:109], v[134:135]
	v_pk_mul_f32 v[110:111], v[110:111], v[138:139]
	v_lshlrev_b32_e32 v134, 16, v182
	v_and_b32_e32 v135, 0xffff0000, v182
	v_max_f32_e32 v134, 0xda24260, v134
	v_max_f32_e32 v135, 0xda24260, v135
	v_rcp_f32_e32 v134, v134
	v_rcp_f32_e32 v135, v135
	v_lshlrev_b32_e32 v136, 16, v178
	v_and_b32_e32 v137, 0xffff0000, v178
	v_lshlrev_b32_e32 v138, 16, v183
	v_and_b32_e32 v139, 0xffff0000, v183
	v_max_f32_e32 v138, 0xda24260, v138
	v_max_f32_e32 v139, 0xda24260, v139
	v_rcp_f32_e32 v138, v138
	v_rcp_f32_e32 v139, v139
	v_lshlrev_b32_e32 v144, 16, v179
	v_and_b32_e32 v145, 0xffff0000, v179
	v_pk_mul_f32 v[134:135], v[134:135], v[136:137]
	v_pk_mul_f32 v[138:139], v[138:139], v[144:145]
	v_pk_mul_f32 v[100:101], v[100:101], v[134:135]
	v_pk_mul_f32 v[102:103], v[102:103], v[138:139]
	v_add_u32_e32 v133, 0x40100, v132
	global_load_dwordx4 v[176:179], v133, s[70:71]
	global_load_dwordx4 v[180:183], v133, s[68:69]
	s_waitcnt vmcnt(12)
; __device__ __forceinline__ float bf_lo(unsigned w) { return __uint_as_float(w << 16); }
; __device__ __forceinline__ float bf_hi(unsigned w) { return __uint_as_float(w & 0xffff0000u); }
;     __device__ __forceinline__ void mid(f32x4 (&acc)[2][2][4][2], const pg8::Unit& u, int wr, int wc, int fr_, int fq_) const {
;         int fr = fr_, fq = fq_; asm volatile("" : "+v"(fr), "+v"(fq));
;         const bf16_t* gm = (const bf16_t*)(ws + WS_GM); const bf16_t* gd = (const bf16_t*)(ws + WS_GD);
;         const int rowbase = u.pm * 256 + wr * 64, cw = wc * 32 + fq * 8;
; #pragma unroll
;         for (int ai = 0; ai < 2; ++ai)
; #pragma unroll
;             for (int m = 0; m < 4; ++m) {
;                 const int row = rowbase + ai * 128 + m * 16 + fr;
; #pragma unroll
;                 for (int bj = 0; bj < 2; ++bj) {
;                     const size_t off = (size_t)row * DM + u.pn * 256 + bj * 128 + cw;
;                     const u32x4 a = *(const u32x4*)(gm + off), b = *(const u32x4*)(gd + off);
;                     f32x4 r0, r1;
;                     r0[0] = bf_lo(a.x) * __builtin_amdgcn_rcpf(fmaxf(bf_lo(b.x), 1e-30f)); r0[1] = bf_hi(a.x) * __builtin_amdgcn_rcpf(fmaxf(bf_hi(b.x), 1e-30f));
;                     r0[2] = bf_lo(a.y) * __builtin_amdgcn_rcpf(fmaxf(bf_lo(b.y), 1e-30f)); r0[3] = bf_hi(a.y) * __builtin_amdgcn_rcpf(fmaxf(bf_hi(b.y), 1e-30f));
;                     r1[0] = bf_lo(a.z) * __builtin_amdgcn_rcpf(fmaxf(bf_lo(b.z), 1e-30f)); r1[1] = bf_hi(a.z) * __builtin_amdgcn_rcpf(fmaxf(bf_hi(b.z), 1e-30f));
;                     r1[2] = bf_lo(a.w) * __builtin_amdgcn_rcpf(fmaxf(bf_lo(b.w), 1e-30f)); r1[3] = bf_hi(a.w) * __builtin_amdgcn_rcpf(fmaxf(bf_hi(b.w), 1e-30f));
;                     acc[ai][bj][m][0] *= r0; acc[ai][bj][m][1] *= r1;
;                 }
;             }
	v_lshlrev_b32_e32 v134, 16, v198
	v_and_b32_e32 v135, 0xffff0000, v198
	v_max_f32_e32 v134, 0xda24260, v134
	v_max_f32_e32 v135, 0xda24260, v135
	v_rcp_f32_e32 v134, v134
	v_rcp_f32_e32 v135, v135
	v_lshlrev_b32_e32 v136, 16, v194
	v_and_b32_e32 v137, 0xffff0000, v194
	v_lshlrev_b32_e32 v138, 16, v199
	v_and_b32_e32 v139, 0xffff0000, v199
	v_max_f32_e32 v138, 0xda24260, v138
	v_max_f32_e32 v139, 0xda24260, v139
	v_rcp_f32_e32 v138, v138
	v_rcp_f32_e32 v139, v139
	v_lshlrev_b32_e32 v144, 16, v195
	v_and_b32_e32 v145, 0xffff0000, v195
	v_pk_mul_f32 v[134:135], v[134:135], v[136:137]
	v_pk_mul_f32 v[138:139], v[138:139], v[144:145]
	v_pk_mul_f32 v[112:113], v[112:113], v[134:135]
	v_pk_mul_f32 v[114:115], v[114:115], v[138:139]
	v_lshlrev_b32_e32 v134, 16, v200
	v_and_b32_e32 v135, 0xffff0000, v200
	v_max_f32_e32 v134, 0xda24260, v134
	v_max_f32_e32 v135, 0xda24260, v135
	v_rcp_f32_e32 v134, v134
	v_rcp_f32_e32 v135, v135
	v_lshlrev_b32_e32 v136, 16, v196
	v_and_b32_e32 v137, 0xffff0000, v196
	v_lshlrev_b32_e32 v138, 16, v201
	v_and_b32_e32 v139, 0xffff0000, v201
	v_max_f32_e32 v138, 0xda24260, v138
	v_max_f32_e32 v139, 0xda24260, v139
	v_rcp_f32_e32 v138, v138
	v_rcp_f32_e32 v139, v139
	v_lshlrev_b32_e32 v144, 16, v197
	v_and_b32_e32 v145, 0xffff0000, v197
	v_pk_mul_f32 v[134:135], v[134:135], v[136:137]
	v_pk_mul_f32 v[138:139], v[138:139], v[144:145]
	v_pk_mul_f32 v[104:105], v[104:105], v[134:135]
	v_pk_mul_f32 v[106:107], v[106:107], v[138:139]
	v_add_u32_e32 v133, 0x48000, v132
	global_load_dwordx4 v[194:197], v133, s[70:71]
	global_load_dwordx4 v[198:201], v133, s[68:69]
	s_waitcnt vmcnt(12)
	v_lshlrev_b32_e32 v134, 16, v206
	v_and_b32_e32 v135, 0xffff0000, v206
	v_max_f32_e32 v134, 0xda24260, v134
	v_max_f32_e32 v135, 0xda24260, v135
	v_rcp_f32_e32 v134, v134
	v_rcp_f32_e32 v135, v135
	v_lshlrev_b32_e32 v136, 16, v202
	v_and_b32_e32 v137, 0xffff0000, v202
	v_lshlrev_b32_e32 v138, 16, v207
	v_and_b32_e32 v139, 0xffff0000, v207
	v_max_f32_e32 v138, 0xda24260, v138
	v_max_f32_e32 v139, 0xda24260, v139
	v_rcp_f32_e32 v138, v138
	v_rcp_f32_e32 v139, v139
	v_lshlrev_b32_e32 v144, 16, v203
	v_and_b32_e32 v145, 0xffff0000, v203
	v_pk_mul_f32 v[134:135], v[134:135], v[136:137]
	v_pk_mul_f32 v[138:139], v[138:139], v[144:145]
	v_pk_mul_f32 v[92:93], v[92:93], v[134:135]
	v_pk_mul_f32 v[94:95], v[94:95], v[138:139]
	v_lshlrev_b32_e32 v134, 16, v208
	v_and_b32_e32 v135, 0xffff0000, v208
	v_max_f32_e32 v134, 0xda24260, v134
	v_max_f32_e32 v135, 0xda24260, v135
	v_rcp_f32_e32 v134, v134
	v_rcp_f32_e32 v135, v135
	v_lshlrev_b32_e32 v136, 16, v204
	v_and_b32_e32 v137, 0xffff0000, v204
	v_lshlrev_b32_e32 v138, 16, v209
	v_and_b32_e32 v139, 0xffff0000, v209
	v_max_f32_e32 v138, 0xda24260, v138
	v_max_f32_e32 v139, 0xda24260, v139
	v_rcp_f32_e32 v138, v138
	v_rcp_f32_e32 v139, v139
	v_lshlrev_b32_e32 v144, 16, v205
	v_and_b32_e32 v145, 0xffff0000, v205
	v_pk_mul_f32 v[134:135], v[134:135], v[136:137]
	v_pk_mul_f32 v[138:139], v[138:139], v[144:145]
	v_pk_mul_f32 v[84:85], v[84:85], v[134:135]
	v_pk_mul_f32 v[86:87], v[86:87], v[138:139]
	v_add_u32_e32 v133, 0x48100, v132
	global_load_dwordx4 v[202:205], v133, s[70:71]
	global_load_dwordx4 v[206:209], v133, s[68:69]
	s_waitcnt vmcnt(12)
	v_lshlrev_b32_e32 v134, 16, v240
	v_and_b32_e32 v135, 0xffff0000, v240
	v_max_f32_e32 v134, 0xda24260, v134
	v_max_f32_e32 v135, 0xda24260, v135
	v_rcp_f32_e32 v134, v134
	v_rcp_f32_e32 v135, v135
	v_lshlrev_b32_e32 v136, 16, v236
	v_and_b32_e32 v137, 0xffff0000, v236
	v_lshlrev_b32_e32 v138, 16, v241
	v_and_b32_e32 v139, 0xffff0000, v241
	v_max_f32_e32 v138, 0xda24260, v138
	v_max_f32_e32 v139, 0xda24260, v139
	v_rcp_f32_e32 v138, v138
	v_rcp_f32_e32 v139, v139
	v_lshlrev_b32_e32 v144, 16, v237
	v_and_b32_e32 v145, 0xffff0000, v237
	v_pk_mul_f32 v[134:135], v[134:135], v[136:137]
	v_pk_mul_f32 v[138:139], v[138:139], v[144:145]
	v_pk_mul_f32 v[96:97], v[96:97], v[134:135]
	v_pk_mul_f32 v[98:99], v[98:99], v[138:139]
	v_lshlrev_b32_e32 v134, 16, v242
	v_and_b32_e32 v135, 0xffff0000, v242
	v_max_f32_e32 v134, 0xda24260, v134
	v_max_f32_e32 v135, 0xda24260, v135
	v_rcp_f32_e32 v134, v134
	v_rcp_f32_e32 v135, v135
	v_lshlrev_b32_e32 v136, 16, v238
	v_and_b32_e32 v137, 0xffff0000, v238
	v_lshlrev_b32_e32 v138, 16, v243
	v_and_b32_e32 v139, 0xffff0000, v243
	v_max_f32_e32 v138, 0xda24260, v138
	v_max_f32_e32 v139, 0xda24260, v139
	v_rcp_f32_e32 v138, v138
	v_rcp_f32_e32 v139, v139
	v_lshlrev_b32_e32 v144, 16, v239
	v_and_b32_e32 v145, 0xffff0000, v239
	v_pk_mul_f32 v[134:135], v[134:135], v[136:137]
	v_pk_mul_f32 v[138:139], v[138:139], v[144:145]
	v_pk_mul_f32 v[88:89], v[88:89], v[134:135]
	v_pk_mul_f32 v[90:91], v[90:91], v[138:139]
	v_add_u32_e32 v133, 0x50000, v132
	global_load_dwordx4 v[236:239], v133, s[70:71]
	global_load_dwordx4 v[240:243], v133, s[68:69]
	s_waitcnt vmcnt(12)
; __device__ __forceinline__ float bf_lo(unsigned w) { return __uint_as_float(w << 16); }
; __device__ __forceinline__ float bf_hi(unsigned w) { return __uint_as_float(w & 0xffff0000u); }
;     __device__ __forceinline__ void mid(f32x4 (&acc)[2][2][4][2], const pg8::Unit& u, int wr, int wc, int fr_, int fq_) const {
;         int fr = fr_, fq = fq_; asm volatile("" : "+v"(fr), "+v"(fq));
;         const bf16_t* gm = (const bf16_t*)(ws + WS_GM); const bf16_t* gd = (const bf16_t*)(ws + WS_GD);
;         const int rowbase = u.pm * 256 + wr * 64, cw = wc * 32 + fq * 8;
; #pragma unroll
;         for (int ai = 0; ai < 2; ++ai)
; #pragma unroll
;             for (int m = 0; m < 4; ++m) {
;                 const int row = rowbase + ai * 128 + m * 16 + fr;
; #pragma unroll
;                 for (int bj = 0; bj < 2; ++bj) {
;                     const size_t off = (size_t)row * DM + u.pn * 256 + bj * 128 + cw;
;                     const u32x4 a = *(const u32x4*)(gm + off), b = *(const u32x4*)(gd + off);
;                     f32x4 r0, r1;
;                     r0[0] = bf_lo(a.x) * __builtin_amdgcn_rcpf(fmaxf(bf_lo(b.x), 1e-30f)); r0[1] = bf_hi(a.x) * __builtin_amdgcn_rcpf(fmaxf(bf_hi(b.x), 1e-30f));
;                     r0[2] = bf_lo(a.y) * __builtin_amdgcn_rcpf(fmaxf(bf_lo(b.y), 1e-30f)); r0[3] = bf_hi(a.y) * __builtin_amdgcn_rcpf(fmaxf(bf_hi(b.y), 1e-30f));
;                     r1[0] = bf_lo(a.z) * __builtin_amdgcn_rcpf(fmaxf(bf_lo(b.z), 1e-30f)); r1[1] = bf_hi(a.z) * __builtin_amdgcn_rcpf(fmaxf(bf_hi(b.z), 1e-30f));
;                     r1[2] = bf_lo(a.w) * __builtin_amdgcn_rcpf(fmaxf(bf_lo(b.w), 1e-30f)); r1[3] = bf_hi(a.w) * __builtin_amdgcn_rcpf(fmaxf(bf_hi(b.w), 1e-30f));
;                     acc[ai][bj][m][0] *= r0; acc[ai][bj][m][1] *= r1;
;                 }
;             }
	v_lshlrev_b32_e32 v134, 16, v248
	v_and_b32_e32 v135, 0xffff0000, v248
	v_max_f32_e32 v134, 0xda24260, v134
	v_max_f32_e32 v135, 0xda24260, v135
	v_rcp_f32_e32 v134, v134
	v_rcp_f32_e32 v135, v135
	v_lshlrev_b32_e32 v136, 16, v244
	v_and_b32_e32 v137, 0xffff0000, v244
	v_lshlrev_b32_e32 v138, 16, v249
	v_and_b32_e32 v139, 0xffff0000, v249
	v_max_f32_e32 v138, 0xda24260, v138
	v_max_f32_e32 v139, 0xda24260, v139
	v_rcp_f32_e32 v138, v138
	v_rcp_f32_e32 v139, v139
	v_lshlrev_b32_e32 v144, 16, v245
	v_and_b32_e32 v145, 0xffff0000, v245
	v_pk_mul_f32 v[134:135], v[134:135], v[136:137]
	v_pk_mul_f32 v[138:139], v[138:139], v[144:145]
	v_pk_mul_f32 v[76:77], v[76:77], v[134:135]
	v_pk_mul_f32 v[78:79], v[78:79], v[138:139]
	v_lshlrev_b32_e32 v134, 16, v250
	v_and_b32_e32 v135, 0xffff0000, v250
	v_max_f32_e32 v134, 0xda24260, v134
	v_max_f32_e32 v135, 0xda24260, v135
	v_rcp_f32_e32 v134, v134
	v_rcp_f32_e32 v135, v135
	v_lshlrev_b32_e32 v136, 16, v246
	v_and_b32_e32 v137, 0xffff0000, v246
	v_lshlrev_b32_e32 v138, 16, v251
	v_and_b32_e32 v139, 0xffff0000, v251
	v_max_f32_e32 v138, 0xda24260, v138
	v_max_f32_e32 v139, 0xda24260, v139
	v_rcp_f32_e32 v138, v138
	v_rcp_f32_e32 v139, v139
	v_lshlrev_b32_e32 v144, 16, v247
	v_and_b32_e32 v145, 0xffff0000, v247
	v_pk_mul_f32 v[134:135], v[134:135], v[136:137]
	v_pk_mul_f32 v[138:139], v[138:139], v[144:145]
	v_pk_mul_f32 v[68:69], v[68:69], v[134:135]
	v_pk_mul_f32 v[70:71], v[70:71], v[138:139]
	v_add_u32_e32 v133, 0x50100, v132
	global_load_dwordx4 v[244:247], v133, s[70:71]
	global_load_dwordx4 v[248:251], v133, s[68:69]
	s_waitcnt vmcnt(12)
	v_lshlrev_b32_e32 v134, 16, v164
	v_and_b32_e32 v135, 0xffff0000, v164
	v_max_f32_e32 v134, 0xda24260, v134
	v_max_f32_e32 v135, 0xda24260, v135
	v_rcp_f32_e32 v134, v134
	v_rcp_f32_e32 v135, v135
	v_lshlrev_b32_e32 v136, 16, v160
	v_and_b32_e32 v137, 0xffff0000, v160
	v_lshlrev_b32_e32 v138, 16, v165
	v_and_b32_e32 v139, 0xffff0000, v165
	v_max_f32_e32 v138, 0xda24260, v138
	v_max_f32_e32 v139, 0xda24260, v139
	v_rcp_f32_e32 v138, v138
	v_rcp_f32_e32 v139, v139
	v_lshlrev_b32_e32 v144, 16, v161
	v_and_b32_e32 v145, 0xffff0000, v161
	v_pk_mul_f32 v[134:135], v[134:135], v[136:137]
	v_pk_mul_f32 v[138:139], v[138:139], v[144:145]
	v_pk_mul_f32 v[80:81], v[80:81], v[134:135]
	v_pk_mul_f32 v[82:83], v[82:83], v[138:139]
	v_lshlrev_b32_e32 v134, 16, v166
	v_and_b32_e32 v135, 0xffff0000, v166
	v_max_f32_e32 v134, 0xda24260, v134
	v_max_f32_e32 v135, 0xda24260, v135
	v_rcp_f32_e32 v134, v134
	v_rcp_f32_e32 v135, v135
	v_lshlrev_b32_e32 v136, 16, v162
	v_and_b32_e32 v137, 0xffff0000, v162
	v_lshlrev_b32_e32 v138, 16, v167
	v_and_b32_e32 v139, 0xffff0000, v167
	v_max_f32_e32 v138, 0xda24260, v138
	v_max_f32_e32 v139, 0xda24260, v139
	v_rcp_f32_e32 v138, v138
	v_rcp_f32_e32 v139, v139
	v_lshlrev_b32_e32 v144, 16, v163
	v_and_b32_e32 v145, 0xffff0000, v163
	v_pk_mul_f32 v[134:135], v[134:135], v[136:137]
	v_pk_mul_f32 v[138:139], v[138:139], v[144:145]
	v_pk_mul_f32 v[72:73], v[72:73], v[134:135]
	v_pk_mul_f32 v[74:75], v[74:75], v[138:139]
	v_add_u32_e32 v133, 0x58000, v132
	global_load_dwordx4 v[160:163], v133, s[70:71]
	global_load_dwordx4 v[164:167], v133, s[68:69]
	s_waitcnt vmcnt(12)
	v_lshlrev_b32_e32 v134, 16, v172
	v_and_b32_e32 v135, 0xffff0000, v172
	v_max_f32_e32 v134, 0xda24260, v134
	v_max_f32_e32 v135, 0xda24260, v135
	v_rcp_f32_e32 v134, v134
	v_rcp_f32_e32 v135, v135
	v_lshlrev_b32_e32 v136, 16, v168
	v_and_b32_e32 v137, 0xffff0000, v168
	v_lshlrev_b32_e32 v138, 16, v173
	v_and_b32_e32 v139, 0xffff0000, v173
	v_max_f32_e32 v138, 0xda24260, v138
	v_max_f32_e32 v139, 0xda24260, v139
	v_rcp_f32_e32 v138, v138
	v_rcp_f32_e32 v139, v139
	v_lshlrev_b32_e32 v144, 16, v169
	v_and_b32_e32 v145, 0xffff0000, v169
	v_pk_mul_f32 v[134:135], v[134:135], v[136:137]
	v_pk_mul_f32 v[138:139], v[138:139], v[144:145]
	v_pk_mul_f32 v[60:61], v[60:61], v[134:135]
	v_pk_mul_f32 v[62:63], v[62:63], v[138:139]
	v_lshlrev_b32_e32 v134, 16, v174
	v_and_b32_e32 v135, 0xffff0000, v174
	v_max_f32_e32 v134, 0xda24260, v134
	v_max_f32_e32 v135, 0xda24260, v135
	v_rcp_f32_e32 v134, v134
	v_rcp_f32_e32 v135, v135
	v_lshlrev_b32_e32 v136, 16, v170
	v_and_b32_e32 v137, 0xffff0000, v170
	v_lshlrev_b32_e32 v138, 16, v175
	v_and_b32_e32 v139, 0xffff0000, v175
	v_max_f32_e32 v138, 0xda24260, v138
	v_max_f32_e32 v139, 0xda24260, v139
	v_rcp_f32_e32 v138, v138
	v_rcp_f32_e32 v139, v139
	v_lshlrev_b32_e32 v144, 16, v171
	v_and_b32_e32 v145, 0xffff0000, v171
	v_pk_mul_f32 v[134:135], v[134:135], v[136:137]
	v_pk_mul_f32 v[138:139], v[138:139], v[144:145]
	v_pk_mul_f32 v[52:53], v[52:53], v[134:135]
	v_pk_mul_f32 v[54:55], v[54:55], v[138:139]
	v_add_u32_e32 v133, 0x58100, v132
	global_load_dwordx4 v[168:171], v133, s[70:71]
	global_load_dwordx4 v[172:175], v133, s[68:69]
	s_waitcnt vmcnt(12)
	v_lshlrev_b32_e32 v134, 16, v180
	v_and_b32_e32 v135, 0xffff0000, v180
	v_max_f32_e32 v134, 0xda24260, v134
	v_max_f32_e32 v135, 0xda24260, v135
	v_rcp_f32_e32 v134, v134
	v_rcp_f32_e32 v135, v135
	v_lshlrev_b32_e32 v136, 16, v176
	v_and_b32_e32 v137, 0xffff0000, v176
	v_lshlrev_b32_e32 v138, 16, v181
	v_and_b32_e32 v139, 0xffff0000, v181
	v_max_f32_e32 v138, 0xda24260, v138
	v_max_f32_e32 v139, 0xda24260, v139
	v_rcp_f32_e32 v138, v138
	v_rcp_f32_e32 v139, v139
	v_lshlrev_b32_e32 v144, 16, v177
	v_and_b32_e32 v145, 0xffff0000, v177
	v_pk_mul_f32 v[134:135], v[134:135], v[136:137]
	v_pk_mul_f32 v[138:139], v[138:139], v[144:145]
	v_pk_mul_f32 v[64:65], v[64:65], v[134:135]
	v_pk_mul_f32 v[66:67], v[66:67], v[138:139]
	v_lshlrev_b32_e32 v134, 16, v182
	v_and_b32_e32 v135, 0xffff0000, v182
	v_max_f32_e32 v134, 0xda24260, v134
	v_max_f32_e32 v135, 0xda24260, v135
	v_rcp_f32_e32 v134, v134
	v_rcp_f32_e32 v135, v135
	v_lshlrev_b32_e32 v136, 16, v178
	v_and_b32_e32 v137, 0xffff0000, v178
	v_lshlrev_b32_e32 v138, 16, v183
	v_and_b32_e32 v139, 0xffff0000, v183
	v_max_f32_e32 v138, 0xda24260, v138
	v_max_f32_e32 v139, 0xda24260, v139
	v_rcp_f32_e32 v138, v138
	v_rcp_f32_e32 v139, v139
	v_lshlrev_b32_e32 v144, 16, v179
	v_and_b32_e32 v145, 0xffff0000, v179
	v_pk_mul_f32 v[134:135], v[134:135], v[136:137]
	v_pk_mul_f32 v[138:139], v[138:139], v[144:145]
	v_pk_mul_f32 v[56:57], v[56:57], v[134:135]
	v_pk_mul_f32 v[58:59], v[58:59], v[138:139]
	s_waitcnt vmcnt(10)
; __device__ __forceinline__ float bf_lo(unsigned w) { return __uint_as_float(w << 16); }
; __device__ __forceinline__ float bf_hi(unsigned w) { return __uint_as_float(w & 0xffff0000u); }
;     __device__ __forceinline__ void mid(f32x4 (&acc)[2][2][4][2], const pg8::Unit& u, int wr, int wc, int fr_, int fq_) const {
;         int fr = fr_, fq = fq_; asm volatile("" : "+v"(fr), "+v"(fq));
;         const bf16_t* gm = (const bf16_t*)(ws + WS_GM); const bf16_t* gd = (const bf16_t*)(ws + WS_GD);
;         const int rowbase = u.pm * 256 + wr * 64, cw = wc * 32 + fq * 8;
; #pragma unroll
;         for (int ai = 0; ai < 2; ++ai)
; #pragma unroll
;             for (int m = 0; m < 4; ++m) {
;                 const int row = rowbase + ai * 128 + m * 16 + fr;
; #pragma unroll
;                 for (int bj = 0; bj < 2; ++bj) {
;                     const size_t off = (size_t)row * DM + u.pn * 256 + bj * 128 + cw;
;                     const u32x4 a = *(const u32x4*)(gm + off), b = *(const u32x4*)(gd + off);
;                     f32x4 r0, r1;
;                     r0[0] = bf_lo(a.x) * __builtin_amdgcn_rcpf(fmaxf(bf_lo(b.x), 1e-30f)); r0[1] = bf_hi(a.x) * __builtin_amdgcn_rcpf(fmaxf(bf_hi(b.x), 1e-30f));
;                     r0[2] = bf_lo(a.y) * __builtin_amdgcn_rcpf(fmaxf(bf_lo(b.y), 1e-30f)); r0[3] = bf_hi(a.y) * __builtin_amdgcn_rcpf(fmaxf(bf_hi(b.y), 1e-30f));
;                     r1[0] = bf_lo(a.z) * __builtin_amdgcn_rcpf(fmaxf(bf_lo(b.z), 1e-30f)); r1[1] = bf_hi(a.z) * __builtin_amdgcn_rcpf(fmaxf(bf_hi(b.z), 1e-30f));
;                     r1[2] = bf_lo(a.w) * __builtin_amdgcn_rcpf(fmaxf(bf_lo(b.w), 1e-30f)); r1[3] = bf_hi(a.w) * __builtin_amdgcn_rcpf(fmaxf(bf_hi(b.w), 1e-30f));
;                     acc[ai][bj][m][0] *= r0; acc[ai][bj][m][1] *= r1;
;                 }
;             }
	v_lshlrev_b32_e32 v134, 16, v198
	v_and_b32_e32 v135, 0xffff0000, v198
	v_max_f32_e32 v134, 0xda24260, v134
	v_max_f32_e32 v135, 0xda24260, v135
	v_rcp_f32_e32 v134, v134
	v_rcp_f32_e32 v135, v135
	v_lshlrev_b32_e32 v136, 16, v194
	v_and_b32_e32 v137, 0xffff0000, v194
	v_lshlrev_b32_e32 v138, 16, v199
	v_and_b32_e32 v139, 0xffff0000, v199
	v_max_f32_e32 v138, 0xda24260, v138
	v_max_f32_e32 v139, 0xda24260, v139
	v_rcp_f32_e32 v138, v138
	v_rcp_f32_e32 v139, v139
	v_lshlrev_b32_e32 v144, 16, v195
	v_and_b32_e32 v145, 0xffff0000, v195
	v_pk_mul_f32 v[134:135], v[134:135], v[136:137]
	v_pk_mul_f32 v[138:139], v[138:139], v[144:145]
	v_pk_mul_f32 v[44:45], v[44:45], v[134:135]
	v_pk_mul_f32 v[46:47], v[46:47], v[138:139]
	v_lshlrev_b32_e32 v134, 16, v200
	v_and_b32_e32 v135, 0xffff0000, v200
	v_max_f32_e32 v134, 0xda24260, v134
	v_max_f32_e32 v135, 0xda24260, v135
	v_rcp_f32_e32 v134, v134
	v_rcp_f32_e32 v135, v135
	v_lshlrev_b32_e32 v136, 16, v196
	v_and_b32_e32 v137, 0xffff0000, v196
	v_lshlrev_b32_e32 v138, 16, v201
	v_and_b32_e32 v139, 0xffff0000, v201
	v_max_f32_e32 v138, 0xda24260, v138
	v_max_f32_e32 v139, 0xda24260, v139
	v_rcp_f32_e32 v138, v138
	v_rcp_f32_e32 v139, v139
	v_lshlrev_b32_e32 v144, 16, v197
	v_and_b32_e32 v145, 0xffff0000, v197
	v_pk_mul_f32 v[134:135], v[134:135], v[136:137]
	v_pk_mul_f32 v[138:139], v[138:139], v[144:145]
	v_pk_mul_f32 v[36:37], v[36:37], v[134:135]
	v_pk_mul_f32 v[38:39], v[38:39], v[138:139]
	s_waitcnt vmcnt(8)
	v_lshlrev_b32_e32 v134, 16, v206
	v_and_b32_e32 v135, 0xffff0000, v206
	v_max_f32_e32 v134, 0xda24260, v134
	v_max_f32_e32 v135, 0xda24260, v135
	v_rcp_f32_e32 v134, v134
	v_rcp_f32_e32 v135, v135
	v_lshlrev_b32_e32 v136, 16, v202
	v_and_b32_e32 v137, 0xffff0000, v202
	v_lshlrev_b32_e32 v138, 16, v207
	v_and_b32_e32 v139, 0xffff0000, v207
	v_max_f32_e32 v138, 0xda24260, v138
	v_max_f32_e32 v139, 0xda24260, v139
	v_rcp_f32_e32 v138, v138
	v_rcp_f32_e32 v139, v139
	v_lshlrev_b32_e32 v144, 16, v203
	v_and_b32_e32 v145, 0xffff0000, v203
	v_pk_mul_f32 v[134:135], v[134:135], v[136:137]
	v_pk_mul_f32 v[138:139], v[138:139], v[144:145]
	v_pk_mul_f32 v[48:49], v[48:49], v[134:135]
	v_pk_mul_f32 v[50:51], v[50:51], v[138:139]
	v_lshlrev_b32_e32 v134, 16, v208
	v_and_b32_e32 v135, 0xffff0000, v208
	v_max_f32_e32 v134, 0xda24260, v134
	v_max_f32_e32 v135, 0xda24260, v135
	v_rcp_f32_e32 v134, v134
	v_rcp_f32_e32 v135, v135
	v_lshlrev_b32_e32 v136, 16, v204
	v_and_b32_e32 v137, 0xffff0000, v204
	v_lshlrev_b32_e32 v138, 16, v209
	v_and_b32_e32 v139, 0xffff0000, v209
	v_max_f32_e32 v138, 0xda24260, v138
	v_max_f32_e32 v139, 0xda24260, v139
	v_rcp_f32_e32 v138, v138
	v_rcp_f32_e32 v139, v139
	v_lshlrev_b32_e32 v144, 16, v205
	v_and_b32_e32 v145, 0xffff0000, v205
	v_pk_mul_f32 v[134:135], v[134:135], v[136:137]
	v_pk_mul_f32 v[138:139], v[138:139], v[144:145]
	v_pk_mul_f32 v[40:41], v[40:41], v[134:135]
	v_pk_mul_f32 v[42:43], v[42:43], v[138:139]
	s_waitcnt vmcnt(6)
	v_lshlrev_b32_e32 v134, 16, v240
	v_and_b32_e32 v135, 0xffff0000, v240
	v_max_f32_e32 v134, 0xda24260, v134
	v_max_f32_e32 v135, 0xda24260, v135
	v_rcp_f32_e32 v134, v134
	v_rcp_f32_e32 v135, v135
	v_lshlrev_b32_e32 v136, 16, v236
	v_and_b32_e32 v137, 0xffff0000, v236
	v_lshlrev_b32_e32 v138, 16, v241
	v_and_b32_e32 v139, 0xffff0000, v241
	v_max_f32_e32 v138, 0xda24260, v138
	v_max_f32_e32 v139, 0xda24260, v139
	v_rcp_f32_e32 v138, v138
	v_rcp_f32_e32 v139, v139
	v_lshlrev_b32_e32 v144, 16, v237
	v_and_b32_e32 v145, 0xffff0000, v237
	v_pk_mul_f32 v[134:135], v[134:135], v[136:137]
	v_pk_mul_f32 v[138:139], v[138:139], v[144:145]
	v_pk_mul_f32 v[28:29], v[28:29], v[134:135]
	v_pk_mul_f32 v[30:31], v[30:31], v[138:139]
	v_lshlrev_b32_e32 v134, 16, v242
	v_and_b32_e32 v135, 0xffff0000, v242
	v_max_f32_e32 v134, 0xda24260, v134
	v_max_f32_e32 v135, 0xda24260, v135
	v_rcp_f32_e32 v134, v134
	v_rcp_f32_e32 v135, v135
	v_lshlrev_b32_e32 v136, 16, v238
	v_and_b32_e32 v137, 0xffff0000, v238
	v_lshlrev_b32_e32 v138, 16, v243
	v_and_b32_e32 v139, 0xffff0000, v243
	v_max_f32_e32 v138, 0xda24260, v138
	v_max_f32_e32 v139, 0xda24260, v139
	v_rcp_f32_e32 v138, v138
	v_rcp_f32_e32 v139, v139
	v_lshlrev_b32_e32 v144, 16, v239
	v_and_b32_e32 v145, 0xffff0000, v239
	v_pk_mul_f32 v[134:135], v[134:135], v[136:137]
	v_pk_mul_f32 v[138:139], v[138:139], v[144:145]
	v_pk_mul_f32 v[20:21], v[20:21], v[134:135]
	v_pk_mul_f32 v[22:23], v[22:23], v[138:139]
	s_waitcnt vmcnt(4)
; __device__ __forceinline__ float bf_lo(unsigned w) { return __uint_as_float(w << 16); }
; __device__ __forceinline__ float bf_hi(unsigned w) { return __uint_as_float(w & 0xffff0000u); }
;     __device__ __forceinline__ void mid(f32x4 (&acc)[2][2][4][2], const pg8::Unit& u, int wr, int wc, int fr_, int fq_) const {
;         int fr = fr_, fq = fq_; asm volatile("" : "+v"(fr), "+v"(fq));
;         const bf16_t* gm = (const bf16_t*)(ws + WS_GM); const bf16_t* gd = (const bf16_t*)(ws + WS_GD);
;         const int rowbase = u.pm * 256 + wr * 64, cw = wc * 32 + fq * 8;
; #pragma unroll
;         for (int ai = 0; ai < 2; ++ai)
; #pragma unroll
;             for (int m = 0; m < 4; ++m) {
;                 const int row = rowbase + ai * 128 + m * 16 + fr;
; #pragma unroll
;                 for (int bj = 0; bj < 2; ++bj) {
;                     const size_t off = (size_t)row * DM + u.pn * 256 + bj * 128 + cw;
;                     const u32x4 a = *(const u32x4*)(gm + off), b = *(const u32x4*)(gd + off);
;                     f32x4 r0, r1;
;                     r0[0] = bf_lo(a.x) * __builtin_amdgcn_rcpf(fmaxf(bf_lo(b.x), 1e-30f)); r0[1] = bf_hi(a.x) * __builtin_amdgcn_rcpf(fmaxf(bf_hi(b.x), 1e-30f));
;                     r0[2] = bf_lo(a.y) * __builtin_amdgcn_rcpf(fmaxf(bf_lo(b.y), 1e-30f)); r0[3] = bf_hi(a.y) * __builtin_amdgcn_rcpf(fmaxf(bf_hi(b.y), 1e-30f));
;                     r1[0] = bf_lo(a.z) * __builtin_amdgcn_rcpf(fmaxf(bf_lo(b.z), 1e-30f)); r1[1] = bf_hi(a.z) * __builtin_amdgcn_rcpf(fmaxf(bf_hi(b.z), 1e-30f));
;                     r1[2] = bf_lo(a.w) * __builtin_amdgcn_rcpf(fmaxf(bf_lo(b.w), 1e-30f)); r1[3] = bf_hi(a.w) * __builtin_amdgcn_rcpf(fmaxf(bf_hi(b.w), 1e-30f));
;                     acc[ai][bj][m][0] *= r0; acc[ai][bj][m][1] *= r1;
;                 }
;             }
	v_lshlrev_b32_e32 v134, 16, v248
	v_and_b32_e32 v135, 0xffff0000, v248
	v_max_f32_e32 v134, 0xda24260, v134
	v_max_f32_e32 v135, 0xda24260, v135
	v_rcp_f32_e32 v134, v134
	v_rcp_f32_e32 v135, v135
	v_lshlrev_b32_e32 v136, 16, v244
	v_and_b32_e32 v137, 0xffff0000, v244
	v_lshlrev_b32_e32 v138, 16, v249
	v_and_b32_e32 v139, 0xffff0000, v249
	v_max_f32_e32 v138, 0xda24260, v138
	v_max_f32_e32 v139, 0xda24260, v139
	v_rcp_f32_e32 v138, v138
	v_rcp_f32_e32 v139, v139
	v_lshlrev_b32_e32 v144, 16, v245
	v_and_b32_e32 v145, 0xffff0000, v245
	v_pk_mul_f32 v[134:135], v[134:135], v[136:137]
	v_pk_mul_f32 v[138:139], v[138:139], v[144:145]
	v_pk_mul_f32 v[32:33], v[32:33], v[134:135]
	v_pk_mul_f32 v[34:35], v[34:35], v[138:139]
	v_lshlrev_b32_e32 v134, 16, v250
	v_and_b32_e32 v135, 0xffff0000, v250
	v_max_f32_e32 v134, 0xda24260, v134
	v_max_f32_e32 v135, 0xda24260, v135
	v_rcp_f32_e32 v134, v134
	v_rcp_f32_e32 v135, v135
	v_lshlrev_b32_e32 v136, 16, v246
	v_and_b32_e32 v137, 0xffff0000, v246
	v_lshlrev_b32_e32 v138, 16, v251
	v_and_b32_e32 v139, 0xffff0000, v251
	v_max_f32_e32 v138, 0xda24260, v138
	v_max_f32_e32 v139, 0xda24260, v139
	v_rcp_f32_e32 v138, v138
	v_rcp_f32_e32 v139, v139
	v_lshlrev_b32_e32 v144, 16, v247
	v_and_b32_e32 v145, 0xffff0000, v247
	v_pk_mul_f32 v[134:135], v[134:135], v[136:137]
	v_pk_mul_f32 v[138:139], v[138:139], v[144:145]
	v_pk_mul_f32 v[24:25], v[24:25], v[134:135]
	v_pk_mul_f32 v[26:27], v[26:27], v[138:139]
	s_waitcnt vmcnt(2)
	v_lshlrev_b32_e32 v134, 16, v164
	v_and_b32_e32 v135, 0xffff0000, v164
	v_max_f32_e32 v134, 0xda24260, v134
	v_max_f32_e32 v135, 0xda24260, v135
	v_rcp_f32_e32 v134, v134
	v_rcp_f32_e32 v135, v135
	v_lshlrev_b32_e32 v136, 16, v160
	v_and_b32_e32 v137, 0xffff0000, v160
	v_lshlrev_b32_e32 v138, 16, v165
	v_and_b32_e32 v139, 0xffff0000, v165
	v_max_f32_e32 v138, 0xda24260, v138
	v_max_f32_e32 v139, 0xda24260, v139
	v_rcp_f32_e32 v138, v138
	v_rcp_f32_e32 v139, v139
	v_lshlrev_b32_e32 v144, 16, v161
	v_and_b32_e32 v145, 0xffff0000, v161
	v_pk_mul_f32 v[134:135], v[134:135], v[136:137]
	v_pk_mul_f32 v[138:139], v[138:139], v[144:145]
	v_pk_mul_f32 v[12:13], v[12:13], v[134:135]
	v_pk_mul_f32 v[14:15], v[14:15], v[138:139]
	v_lshlrev_b32_e32 v134, 16, v166
	v_and_b32_e32 v135, 0xffff0000, v166
	v_max_f32_e32 v134, 0xda24260, v134
	v_max_f32_e32 v135, 0xda24260, v135
	v_rcp_f32_e32 v134, v134
	v_rcp_f32_e32 v135, v135
	v_lshlrev_b32_e32 v136, 16, v162
	v_and_b32_e32 v137, 0xffff0000, v162
	v_lshlrev_b32_e32 v138, 16, v167
	v_and_b32_e32 v139, 0xffff0000, v167
	v_max_f32_e32 v138, 0xda24260, v138
	v_max_f32_e32 v139, 0xda24260, v139
	v_rcp_f32_e32 v138, v138
	v_rcp_f32_e32 v139, v139
	v_lshlrev_b32_e32 v144, 16, v163
	v_and_b32_e32 v145, 0xffff0000, v163
	v_pk_mul_f32 v[134:135], v[134:135], v[136:137]
	v_pk_mul_f32 v[138:139], v[138:139], v[144:145]
	v_pk_mul_f32 v[4:5], v[4:5], v[134:135]
	v_pk_mul_f32 v[6:7], v[6:7], v[138:139]
	s_waitcnt vmcnt(0)
	v_lshlrev_b32_e32 v134, 16, v172
	v_and_b32_e32 v135, 0xffff0000, v172
	v_max_f32_e32 v134, 0xda24260, v134
	v_max_f32_e32 v135, 0xda24260, v135
	v_rcp_f32_e32 v134, v134
	v_rcp_f32_e32 v135, v135
	v_lshlrev_b32_e32 v136, 16, v168
	v_and_b32_e32 v137, 0xffff0000, v168
	v_lshlrev_b32_e32 v138, 16, v173
	v_and_b32_e32 v139, 0xffff0000, v173
	v_max_f32_e32 v138, 0xda24260, v138
	v_max_f32_e32 v139, 0xda24260, v139
	v_rcp_f32_e32 v138, v138
	v_rcp_f32_e32 v139, v139
	v_lshlrev_b32_e32 v144, 16, v169
	v_and_b32_e32 v145, 0xffff0000, v169
	v_pk_mul_f32 v[134:135], v[134:135], v[136:137]
	v_pk_mul_f32 v[138:139], v[138:139], v[144:145]
	v_pk_mul_f32 v[16:17], v[16:17], v[134:135]
	v_pk_mul_f32 v[18:19], v[18:19], v[138:139]
	v_lshlrev_b32_e32 v134, 16, v174
	v_and_b32_e32 v135, 0xffff0000, v174
	v_max_f32_e32 v134, 0xda24260, v134
	v_max_f32_e32 v135, 0xda24260, v135
	v_rcp_f32_e32 v134, v134
	v_rcp_f32_e32 v135, v135
	v_lshlrev_b32_e32 v136, 16, v170
	v_and_b32_e32 v137, 0xffff0000, v170
	v_lshlrev_b32_e32 v138, 16, v175
	v_and_b32_e32 v139, 0xffff0000, v175
	v_max_f32_e32 v138, 0xda24260, v138
	v_max_f32_e32 v139, 0xda24260, v139
	v_rcp_f32_e32 v138, v138
	v_rcp_f32_e32 v139, v139
	v_lshlrev_b32_e32 v144, 16, v171
	v_and_b32_e32 v145, 0xffff0000, v171
	v_pk_mul_f32 v[134:135], v[134:135], v[136:137]
	v_pk_mul_f32 v[138:139], v[138:139], v[144:145]
	v_pk_mul_f32 v[8:9], v[8:9], v[134:135]
	v_pk_mul_f32 v[10:11], v[10:11], v[138:139]
	s_branch .LBB0_397
